# retention: all MFMA blocks (X, C/S, T) with software-pipelined LDS reads, bit-identical math
# baseline (speedup 1.0000x reference)
.LBB0_598:
	ds_read_b128 v[154:157], v246
	ds_read_b128 v[160:163], v247
	ds_read_b128 v[164:167], v246 offset:32
	ds_read_b128 v[194:197], v247 offset:32
	ds_read_b64_tr_b16 v[198:199], v225 offset:34816
	ds_read_b64_tr_b16 v[200:201], v225 offset:35088
	ds_read_b64_tr_b16 v[206:207], v248
	ds_read_b64_tr_b16 v[208:209], v248 offset:144
	v_mov_b32_e32 v177, v176
	v_pk_mul_f32 v[18:19], v[190:191], v[18:19]
	s_waitcnt lgkmcnt(6)
	v_mfma_f32_32x32x16_bf16 v[50:65], v[154:157], v[160:163], 0
	v_mul_f32_e64 v32, v176, v32
	v_mul_f32_e64 v33, v177, v33
	v_mul_f32_e64 v30, v176, v30
	v_mul_f32_e64 v31, v177, v31
	v_mul_f32_e64 v28, v176, v28
	v_mul_f32_e64 v29, v177, v29
	v_pk_mul_f32 v[26:27], v[176:177], v[26:27]
	v_pk_mul_f32 v[24:25], v[176:177], v[24:25]
	v_pk_mul_f32 v[22:23], v[176:177], v[22:23]
	v_pk_mul_f32 v[20:21], v[176:177], v[20:21]
	ds_read_b128 v[210:213], v246 offset:64
	ds_read_b128 v[214:217], v247 offset:64
	s_waitcnt lgkmcnt(6)
	v_mfma_f32_32x32x16_bf16 v[50:65], v[164:167], v[194:197], v[50:65]
	ds_read_b64_tr_b16 v[154:155], v225 offset:39168
	ds_read_b64_tr_b16 v[156:157], v225 offset:39440
	ds_read_b64_tr_b16 v[160:161], v248 offset:2304
	ds_read_b64_tr_b16 v[162:163], v248 offset:2448
	s_waitcnt lgkmcnt(6)
	v_mfma_f32_32x32x16_bf16 v[18:33], v[198:201], v[206:209], v[18:33]
	ds_read_b128 v[164:167], v246 offset:96
	ds_read_b128 v[194:197], v247 offset:96
	s_waitcnt lgkmcnt(6)
	v_mfma_f32_32x32x16_bf16 v[50:65], v[210:213], v[214:217], v[50:65]
	s_cmp_lg_u32 s85, 1
	s_cselect_b64 s[74:75], -1, 0
	s_cmp_eq_u32 s85, 1
	ds_read_b64_tr_b16 v[198:199], v225 offset:43520
	ds_read_b64_tr_b16 v[200:201], v225 offset:43792
	ds_read_b64_tr_b16 v[206:207], v248 offset:4608
	ds_read_b64_tr_b16 v[208:209], v248 offset:4752
	s_waitcnt lgkmcnt(6)
	v_mfma_f32_32x32x16_bf16 v[18:33], v[154:157], v[160:163], v[18:33]
	ds_read_b128 v[210:213], v246 offset:128
	ds_read_b128 v[214:217], v247 offset:128
	s_waitcnt lgkmcnt(6)
	v_mfma_f32_32x32x16_bf16 v[50:65], v[164:167], v[194:197], v[50:65]
	ds_read_b64_tr_b16 v[154:155], v225 offset:47872
	ds_read_b64_tr_b16 v[156:157], v225 offset:48144
	ds_read_b64_tr_b16 v[160:161], v248 offset:6912
	ds_read_b64_tr_b16 v[162:163], v248 offset:7056
	s_waitcnt lgkmcnt(6)
	v_mfma_f32_32x32x16_bf16 v[18:33], v[198:201], v[206:209], v[18:33]
	ds_read_b128 v[164:167], v246 offset:160
	ds_read_b128 v[194:197], v247 offset:160
	s_waitcnt lgkmcnt(6)
	v_mfma_f32_32x32x16_bf16 v[50:65], v[210:213], v[214:217], v[50:65]
	ds_read_b64_tr_b16 v[198:199], v225 offset:52224
	ds_read_b64_tr_b16 v[200:201], v225 offset:52496
	ds_read_b64_tr_b16 v[206:207], v248 offset:9216
	ds_read_b64_tr_b16 v[208:209], v248 offset:9360
	s_waitcnt lgkmcnt(6)
	v_mfma_f32_32x32x16_bf16 v[18:33], v[154:157], v[160:163], v[18:33]
	ds_read_b64_tr_b16 v[210:211], v225 offset:56576
	ds_read_b64_tr_b16 v[212:213], v225 offset:56848
	ds_read_b64_tr_b16 v[214:215], v248 offset:11520
	ds_read_b64_tr_b16 v[216:217], v248 offset:11664
	s_waitcnt lgkmcnt(8)
	v_mfma_f32_32x32x16_bf16 v[50:65], v[164:167], v[194:197], v[50:65]
	ds_read_b128 v[4:7], v246 offset:192
	ds_read_b128 v[8:11], v246 offset:224
	ds_read_b128 v[102:105], v247 offset:192
	ds_read_b128 v[106:109], v247 offset:224
	s_waitcnt lgkmcnt(8)
	v_mfma_f32_32x32x16_bf16 v[18:33], v[198:201], v[206:209], v[18:33]
	ds_read_b64_tr_b16 v[12:13], v225 offset:60928
	ds_read_b64_tr_b16 v[14:15], v225 offset:61200
	ds_read_b64_tr_b16 v[98:99], v225 offset:65280
	ds_read_b64_tr_b16 v[100:101], v226 offset:30736
	s_waitcnt lgkmcnt(8)
	v_mfma_f32_32x32x16_bf16 v[18:33], v[210:213], v[214:217], v[18:33]
	ds_read_b64_tr_b16 v[110:111], v248 offset:13824
	ds_read_b64_tr_b16 v[112:113], v248 offset:13968
	ds_read_b64_tr_b16 v[202:203], v248 offset:16128
	ds_read_b64_tr_b16 v[204:205], v248 offset:16272
	s_waitcnt lgkmcnt(0)
	s_barrier
	s_waitcnt vmcnt(3)
	ds_write_b128 v223, v[114:117]
	ds_write_b128 v223, v[130:133] offset:34816
	s_waitcnt vmcnt(2)
	ds_write_b128 v223, v[118:121] offset:8704
	ds_write_b128 v223, v[138:141] offset:43520
	s_waitcnt vmcnt(1)
	ds_write_b128 v223, v[134:137] offset:17408
	ds_write_b128 v223, v[146:149] offset:52224
	s_waitcnt vmcnt(0)
	ds_write_b128 v223, v[142:145] offset:26112
	ds_write_b128 v223, v[150:153] offset:60928
	v_mfma_f32_32x32x16_bf16 v[18:33], v[12:15], v[110:113], v[18:33]
	v_mfma_f32_32x32x16_bf16 v[50:65], v[4:7], v[102:105], v[50:65]
	v_mfma_f32_32x32x16_bf16 v[18:33], v[98:101], v[202:205], v[18:33]
	v_mfma_f32_32x32x16_bf16 v[50:65], v[8:11], v[106:109], v[50:65]
	s_nop 10
	v_cvt_pk_bf16_f32 v12, v18, v19
	v_cvt_pk_bf16_f32 v13, v20, v21
	v_cvt_pk_bf16_f32 v14, v22, v23
	v_cvt_pk_bf16_f32 v15, v24, v25
	v_cvt_pk_bf16_f32 v4, v26, v27
	v_cvt_pk_bf16_f32 v5, v28, v29
	v_cvt_pk_bf16_f32 v6, v30, v31
	v_cvt_pk_bf16_f32 v7, v32, v33
	ds_write2_b64 v169, v[12:13], v[14:15] offset1:2
	ds_write2_b64 v169, v[4:5], v[6:7] offset0:4 offset1:6
	s_cbranch_scc1 .LBB0_600
	v_add_co_u32_e32 v4, vcc, 0x7a40000, v192
	s_nop 1
	v_addc_co_u32_e32 v5, vcc, 0, v193, vcc
	v_add_co_u32_e32 v6, vcc, 0xba40000, v192
	s_nop 1
	v_addc_co_u32_e32 v7, vcc, 0, v193, vcc
	global_load_dwordx4 v[114:117], v[4:5], off
	global_load_dwordx4 v[130:133], v[6:7], off
	v_add_co_u32_e32 v4, vcc, 0x7a50000, v192
	s_nop 1
	v_addc_co_u32_e32 v5, vcc, 0, v193, vcc
	v_add_co_u32_e32 v6, vcc, 0xba50000, v192
	s_nop 1
	v_addc_co_u32_e32 v7, vcc, 0, v193, vcc
	global_load_dwordx4 v[118:121], v[4:5], off
	global_load_dwordx4 v[138:141], v[6:7], off
	v_add_co_u32_e32 v4, vcc, 0x7a60000, v192
	s_nop 1
	v_addc_co_u32_e32 v5, vcc, 0, v193, vcc
	v_add_co_u32_e32 v6, vcc, 0xba60000, v192
	s_nop 1
	v_addc_co_u32_e32 v7, vcc, 0, v193, vcc
	global_load_dwordx4 v[134:137], v[4:5], off
	global_load_dwordx4 v[146:149], v[6:7], off
	v_add_co_u32_e32 v4, vcc, 0x7a70000, v192
	s_nop 1
	v_addc_co_u32_e32 v5, vcc, 0, v193, vcc
	v_add_co_u32_e32 v6, vcc, 0xba70000, v192
	s_nop 1
	v_addc_co_u32_e32 v7, vcc, 0, v193, vcc
	global_load_dwordx4 v[142:145], v[4:5], off
	global_load_dwordx4 v[150:153], v[6:7], off
	v_lshl_add_u64 v[4:5], s[82:83], 0, v[180:181]
	v_add_co_u32_e32 v6, vcc, 0xfa80000, v4
	s_nop 1
	v_addc_co_u32_e32 v7, vcc, 0, v5, vcc
	v_add_co_u32_e32 v4, vcc, 0xfac0000, v4
	s_nop 1
	v_addc_co_u32_e32 v5, vcc, 0, v5, vcc
	global_load_dwordx4 v[122:125], v[6:7], off
	global_load_dwordx4 v[126:129], v[4:5], off

.LBB0_604:
	ds_read_b128 v[154:157], v246
	ds_read_b128 v[160:163], v247 offset:256
	ds_read_b128 v[164:167], v246 offset:32
	ds_read_b128 v[194:197], v247 offset:288
	ds_read_b64_tr_b16 v[198:199], v225 offset:34816
	ds_read_b64_tr_b16 v[200:201], v225 offset:35088
	ds_read_b64_tr_b16 v[206:207], v248
	ds_read_b64_tr_b16 v[208:209], v248 offset:144
	v_mov_b32_e32 v177, v176
	v_pk_mul_f32 v[48:49], v[176:177], v[48:49]
	v_pk_mul_f32 v[46:47], v[176:177], v[46:47]
	s_waitcnt lgkmcnt(6)
	v_mfma_f32_32x32x16_bf16 v[50:65], v[154:157], v[160:163], v[50:65]
	v_mul_f32_e64 v44, v176, v44
	v_mul_f32_e64 v45, v177, v45
	v_mul_f32_e64 v42, v176, v42
	v_mul_f32_e64 v43, v177, v43
	v_mul_f32_e64 v40, v176, v40
	v_mul_f32_e64 v41, v177, v41
	v_pk_mul_f32 v[38:39], v[176:177], v[38:39]
	v_pk_mul_f32 v[36:37], v[176:177], v[36:37]
	v_pk_mul_f32 v[34:35], v[190:191], v[34:35]
	v_cndmask_b32_e64 v3, v98, 0, s[4:5]
	ds_read_b128 v[210:213], v246 offset:64
	ds_read_b128 v[214:217], v247 offset:320
	s_waitcnt lgkmcnt(6)
	v_mfma_f32_32x32x16_bf16 v[50:65], v[164:167], v[194:197], v[50:65]
	ds_read_b64_tr_b16 v[154:155], v225 offset:39168
	ds_read_b64_tr_b16 v[156:157], v225 offset:39440
	ds_read_b64_tr_b16 v[160:161], v248 offset:2304
	ds_read_b64_tr_b16 v[162:163], v248 offset:2448
	s_waitcnt lgkmcnt(6)
	v_mfma_f32_32x32x16_bf16 v[34:49], v[198:201], v[206:209], v[34:49]
	ds_read_b128 v[164:167], v246 offset:96
	ds_read_b128 v[194:197], v247 offset:352
	s_waitcnt lgkmcnt(6)
	v_mfma_f32_32x32x16_bf16 v[50:65], v[210:213], v[214:217], v[50:65]
	s_andn2_b64 vcc, exec, s[80:81]
	ds_read_b64_tr_b16 v[198:199], v225 offset:43520
	ds_read_b64_tr_b16 v[200:201], v225 offset:43792
	ds_read_b64_tr_b16 v[206:207], v248 offset:4608
	ds_read_b64_tr_b16 v[208:209], v248 offset:4752
	s_waitcnt lgkmcnt(6)
	v_mfma_f32_32x32x16_bf16 v[34:49], v[154:157], v[160:163], v[34:49]
	ds_read_b128 v[210:213], v246 offset:128
	ds_read_b128 v[214:217], v247 offset:384
	s_waitcnt lgkmcnt(6)
	v_mfma_f32_32x32x16_bf16 v[50:65], v[164:167], v[194:197], v[50:65]
	ds_read_b64_tr_b16 v[154:155], v225 offset:47872
	ds_read_b64_tr_b16 v[156:157], v225 offset:48144
	ds_read_b64_tr_b16 v[160:161], v248 offset:6912
	ds_read_b64_tr_b16 v[162:163], v248 offset:7056
	s_waitcnt lgkmcnt(6)
	v_mfma_f32_32x32x16_bf16 v[34:49], v[198:201], v[206:209], v[34:49]
	ds_read_b128 v[164:167], v246 offset:160
	ds_read_b128 v[194:197], v247 offset:416
	s_waitcnt lgkmcnt(6)
	v_mfma_f32_32x32x16_bf16 v[50:65], v[210:213], v[214:217], v[50:65]
	ds_read_b64_tr_b16 v[198:199], v225 offset:52224
	ds_read_b64_tr_b16 v[200:201], v225 offset:52496
	ds_read_b64_tr_b16 v[206:207], v248 offset:9216
	ds_read_b64_tr_b16 v[208:209], v248 offset:9360
	s_waitcnt lgkmcnt(6)
	v_mfma_f32_32x32x16_bf16 v[34:49], v[154:157], v[160:163], v[34:49]
	ds_read_b128 v[210:213], v246 offset:192
	ds_read_b128 v[214:217], v247 offset:448
	s_waitcnt lgkmcnt(6)
	v_mfma_f32_32x32x16_bf16 v[50:65], v[164:167], v[194:197], v[50:65]
	ds_read_b64_tr_b16 v[154:155], v225 offset:56576
	ds_read_b64_tr_b16 v[156:157], v225 offset:56848
	ds_read_b64_tr_b16 v[160:161], v248 offset:11520
	ds_read_b64_tr_b16 v[162:163], v248 offset:11664
	s_waitcnt lgkmcnt(6)
	v_mfma_f32_32x32x16_bf16 v[34:49], v[198:201], v[206:209], v[34:49]
	ds_read_b128 v[164:167], v246 offset:224
	ds_read_b128 v[194:197], v247 offset:480
	s_waitcnt lgkmcnt(6)
	v_mfma_f32_32x32x16_bf16 v[50:65], v[210:213], v[214:217], v[50:65]
	ds_read_b64_tr_b16 v[198:199], v225 offset:60928
	ds_read_b64_tr_b16 v[200:201], v225 offset:61200
	ds_read_b64_tr_b16 v[206:207], v248 offset:13824
	ds_read_b64_tr_b16 v[208:209], v248 offset:13968
	s_waitcnt lgkmcnt(6)
	v_mfma_f32_32x32x16_bf16 v[34:49], v[154:157], v[160:163], v[34:49]
	ds_read_b64_tr_b16 v[4:5], v225 offset:65280
	ds_read_b64_tr_b16 v[6:7], v226 offset:30736
	s_waitcnt lgkmcnt(6)
	v_mfma_f32_32x32x16_bf16 v[50:65], v[164:167], v[194:197], v[50:65]
	ds_read_b64_tr_b16 v[8:9], v248 offset:16128
	s_waitcnt lgkmcnt(3)
	v_mfma_f32_32x32x16_bf16 v[34:49], v[198:201], v[206:209], v[34:49]
	ds_read_b64_tr_b16 v[10:11], v248 offset:16272
	s_waitcnt lgkmcnt(0)
	s_barrier
	v_mfma_f32_32x32x16_bf16 v[34:49], v[4:7], v[8:11], v[34:49]
	v_cndmask_b32_e64 v8, v104, 0, s[16:17]
	v_cndmask_b32_e64 v9, v105, 0, s[18:19]
	s_nop 9
	v_cvt_pk_bf16_f32 v4, v34, v35
	v_cvt_pk_bf16_f32 v5, v36, v37
	v_cvt_pk_bf16_f32 v6, v38, v39
	v_cvt_pk_bf16_f32 v7, v40, v41
	ds_write2_b64 v169, v[4:5], v[6:7] offset0:32 offset1:34
	v_cvt_pk_bf16_f32 v4, v42, v43
	v_cvt_pk_bf16_f32 v5, v44, v45
	v_cvt_pk_bf16_f32 v6, v46, v47
	v_cvt_pk_bf16_f32 v7, v48, v49
	ds_write2_b64 v169, v[4:5], v[6:7] offset0:36 offset1:38
	v_cndmask_b32_e64 v5, v100, 0, s[8:9]
	v_cndmask_b32_e64 v6, v101, 0, s[10:11]
	v_cndmask_b32_e64 v4, 0, v99, s[6:7]
	v_cvt_pk_bf16_f32 v5, v5, v6
	v_cndmask_b32_e64 v6, v102, 0, s[12:13]
	v_cndmask_b32_e64 v7, v103, 0, s[14:15]
	v_cvt_pk_bf16_f32 v4, v3, v4
	v_add_u32_e32 v3, v171, v227
	v_cvt_pk_bf16_f32 v6, v6, v7
	v_cvt_pk_bf16_f32 v7, v8, v9
	ds_write2_b64 v3, v[4:5], v[6:7] offset1:2
	v_cndmask_b32_e64 v4, v106, 0, s[20:21]
	v_cndmask_b32_e64 v5, v107, 0, s[22:23]
	v_cndmask_b32_e64 v6, v108, 0, s[24:25]
	v_cndmask_b32_e64 v7, v109, 0, s[26:27]
	v_cvt_pk_bf16_f32 v4, v4, v5
	v_cvt_pk_bf16_f32 v5, v6, v7
	v_cndmask_b32_e64 v6, v110, 0, s[28:29]
	v_cndmask_b32_e64 v7, v111, 0, s[30:31]
	v_cndmask_b32_e64 v8, v112, 0, s[34:35]
	v_cndmask_b32_e64 v9, v113, 0, s[36:37]
	v_cvt_pk_bf16_f32 v6, v6, v7
	v_cvt_pk_bf16_f32 v7, v8, v9
	ds_write2_b64 v3, v[4:5], v[6:7] offset0:4 offset1:6
	s_cbranch_vccnz .LBB0_606
	v_cndmask_b32_e64 v3, v66, 0, s[38:39]
	v_cndmask_b32_e64 v4, 0, v67, s[40:41]
	v_cndmask_b32_e64 v5, v68, 0, s[42:43]
	v_cndmask_b32_e64 v6, v69, 0, s[44:45]
	v_cvt_pk_bf16_f32 v4, v3, v4
	v_cvt_pk_bf16_f32 v5, v5, v6
	v_cndmask_b32_e64 v3, v70, 0, s[46:47]
	v_cndmask_b32_e64 v6, v71, 0, s[48:49]
	v_cndmask_b32_e64 v7, v72, 0, s[50:51]
	v_cndmask_b32_e64 v8, v73, 0, s[52:53]
	v_cvt_pk_bf16_f32 v6, v3, v6
	v_cvt_pk_bf16_f32 v7, v7, v8
	ds_write2_b64 v244, v[4:5], v[6:7] offset1:2
	v_cndmask_b32_e64 v3, v74, 0, s[54:55]
	v_cndmask_b32_e64 v4, v75, 0, s[56:57]
	v_cndmask_b32_e64 v5, v76, 0, s[58:59]
	v_cndmask_b32_e64 v6, v77, 0, s[60:61]
	v_cvt_pk_bf16_f32 v4, v3, v4
	v_cvt_pk_bf16_f32 v5, v5, v6
	v_cndmask_b32_e64 v3, v78, 0, s[62:63]
	v_cndmask_b32_e64 v6, v79, 0, s[64:65]
	v_cndmask_b32_e64 v7, v80, 0, s[66:67]
	v_cndmask_b32_e64 v8, v81, 0, s[68:69]
	v_cvt_pk_bf16_f32 v6, v3, v6
	v_cvt_pk_bf16_f32 v7, v7, v8
	ds_write2_b64 v244, v[4:5], v[6:7] offset0:4 offset1:6
.LBB0_606:
	s_waitcnt lgkmcnt(0)
	s_barrier
	s_and_b64 vcc, exec, s[76:77]
	s_cbranch_vccnz .Lmy_t8
	s_and_b64 vcc, exec, s[78:79]
	s_cbranch_vccnz .Lmy_t6
	s_and_b64 vcc, exec, s[72:73]
	s_cbranch_vccnz .Lmy_t4
	ds_read_b128 v[4:7], v249
	ds_read_b64_tr_b16 v[8:9], v250
	ds_read_b64_tr_b16 v[10:11], v250 offset:576
	ds_read_b128 v[154:157], v249 offset:32
	ds_read_b64_tr_b16 v[160:161], v250 offset:2304
	ds_read_b64_tr_b16 v[162:163], v250 offset:2880
	s_waitcnt lgkmcnt(3)
	v_mfma_f32_32x32x16_bf16 v[66:81], v[4:7], v[8:11], 0
	s_waitcnt lgkmcnt(0)
	v_mfma_f32_32x32x16_bf16 v[66:81], v[154:157], v[160:163], v[66:81]
	s_branch .LBB0_610
.Lmy_t4:
	ds_read_b128 v[4:7], v249
	ds_read_b64_tr_b16 v[8:9], v250
	ds_read_b64_tr_b16 v[10:11], v250 offset:576
	ds_read_b128 v[154:157], v249 offset:32
	ds_read_b64_tr_b16 v[160:161], v250 offset:2304
	ds_read_b64_tr_b16 v[162:163], v250 offset:2880
	ds_read_b128 v[164:167], v249 offset:64
	ds_read_b64_tr_b16 v[194:195], v250 offset:4608
	ds_read_b64_tr_b16 v[196:197], v250 offset:5184
	ds_read_b128 v[198:201], v249 offset:96
	ds_read_b64_tr_b16 v[206:207], v250 offset:6912
	ds_read_b64_tr_b16 v[208:209], v250 offset:7488
	s_waitcnt lgkmcnt(9)
	v_mfma_f32_32x32x16_bf16 v[66:81], v[4:7], v[8:11], 0
	s_waitcnt lgkmcnt(6)
	v_mfma_f32_32x32x16_bf16 v[66:81], v[154:157], v[160:163], v[66:81]
	s_waitcnt lgkmcnt(3)
	v_mfma_f32_32x32x16_bf16 v[66:81], v[164:167], v[194:197], v[66:81]
	s_waitcnt lgkmcnt(0)
	v_mfma_f32_32x32x16_bf16 v[66:81], v[198:201], v[206:209], v[66:81]
	s_branch .LBB0_610
.Lmy_t6:
	ds_read_b128 v[4:7], v249
	ds_read_b64_tr_b16 v[8:9], v250
	ds_read_b64_tr_b16 v[10:11], v250 offset:576
	ds_read_b128 v[154:157], v249 offset:32
	ds_read_b64_tr_b16 v[160:161], v250 offset:2304
	ds_read_b64_tr_b16 v[162:163], v250 offset:2880
	ds_read_b128 v[164:167], v249 offset:64
	ds_read_b64_tr_b16 v[194:195], v250 offset:4608
	ds_read_b64_tr_b16 v[196:197], v250 offset:5184
	ds_read_b128 v[198:201], v249 offset:96
	ds_read_b64_tr_b16 v[206:207], v250 offset:6912
	ds_read_b64_tr_b16 v[208:209], v250 offset:7488
	s_waitcnt lgkmcnt(9)
	v_mfma_f32_32x32x16_bf16 v[66:81], v[4:7], v[8:11], 0
	ds_read_b128 v[4:7], v249 offset:128
	ds_read_b64_tr_b16 v[8:9], v250 offset:9216
	ds_read_b64_tr_b16 v[10:11], v250 offset:9792
	s_waitcnt lgkmcnt(9)
	v_mfma_f32_32x32x16_bf16 v[66:81], v[154:157], v[160:163], v[66:81]
	ds_read_b128 v[154:157], v249 offset:160
	ds_read_b64_tr_b16 v[160:161], v250 offset:11520
	ds_read_b64_tr_b16 v[162:163], v250 offset:12096
	s_waitcnt lgkmcnt(9)
	v_mfma_f32_32x32x16_bf16 v[66:81], v[164:167], v[194:197], v[66:81]
	s_waitcnt lgkmcnt(6)
	v_mfma_f32_32x32x16_bf16 v[66:81], v[198:201], v[206:209], v[66:81]
	s_waitcnt lgkmcnt(3)
	v_mfma_f32_32x32x16_bf16 v[66:81], v[4:7], v[8:11], v[66:81]
	s_waitcnt lgkmcnt(0)
	v_mfma_f32_32x32x16_bf16 v[66:81], v[154:157], v[160:163], v[66:81]
	s_branch .LBB0_610
.Lmy_t8:
	ds_read_b128 v[4:7], v249
	ds_read_b64_tr_b16 v[8:9], v250
	ds_read_b64_tr_b16 v[10:11], v250 offset:576
	ds_read_b128 v[154:157], v249 offset:32
	ds_read_b64_tr_b16 v[160:161], v250 offset:2304
	ds_read_b64_tr_b16 v[162:163], v250 offset:2880
	ds_read_b128 v[164:167], v249 offset:64
	ds_read_b64_tr_b16 v[194:195], v250 offset:4608
	ds_read_b64_tr_b16 v[196:197], v250 offset:5184
	ds_read_b128 v[198:201], v249 offset:96
	ds_read_b64_tr_b16 v[206:207], v250 offset:6912
	ds_read_b64_tr_b16 v[208:209], v250 offset:7488
	s_waitcnt lgkmcnt(9)
	v_mfma_f32_32x32x16_bf16 v[66:81], v[4:7], v[8:11], 0
	ds_read_b128 v[4:7], v249 offset:128
	ds_read_b64_tr_b16 v[8:9], v250 offset:9216
	ds_read_b64_tr_b16 v[10:11], v250 offset:9792
	s_waitcnt lgkmcnt(9)
	v_mfma_f32_32x32x16_bf16 v[66:81], v[154:157], v[160:163], v[66:81]
	ds_read_b128 v[154:157], v249 offset:160
	ds_read_b64_tr_b16 v[160:161], v250 offset:11520
	ds_read_b64_tr_b16 v[162:163], v250 offset:12096
	s_waitcnt lgkmcnt(9)
	v_mfma_f32_32x32x16_bf16 v[66:81], v[164:167], v[194:197], v[66:81]
	ds_read_b128 v[164:167], v249 offset:192
	ds_read_b64_tr_b16 v[194:195], v250 offset:13824
	ds_read_b64_tr_b16 v[196:197], v250 offset:14400
	s_waitcnt lgkmcnt(9)
	v_mfma_f32_32x32x16_bf16 v[66:81], v[198:201], v[206:209], v[66:81]
	ds_read_b128 v[198:201], v249 offset:224
	ds_read_b64_tr_b16 v[206:207], v250 offset:16128
	ds_read_b64_tr_b16 v[208:209], v250 offset:16704
	s_waitcnt lgkmcnt(9)
	v_mfma_f32_32x32x16_bf16 v[66:81], v[4:7], v[8:11], v[66:81]
	s_waitcnt lgkmcnt(6)
	v_mfma_f32_32x32x16_bf16 v[66:81], v[154:157], v[160:163], v[66:81]
	s_waitcnt lgkmcnt(3)
	v_mfma_f32_32x32x16_bf16 v[66:81], v[164:167], v[194:197], v[66:81]
	s_waitcnt lgkmcnt(0)
	v_mfma_f32_32x32x16_bf16 v[66:81], v[198:201], v[206:209], v[66:81]

.LBB0_612:
	v_mul_f32_e32 v4, v228, v3
	v_exp_f32_e32 v7, v4
	v_lshl_add_u64 v[4:5], s[82:83], 0, v[184:185]
	v_add_co_u32_e32 v6, vcc, 0xfa00000, v4
	v_mul_f32_e32 v8, v176, v7
	v_mul_f32_e32 v8, v50, v8
	s_nop 1
	v_fmac_f32_e32 v8, v66, v7
	v_bfe_u32 v7, v8, 16, 1
	v_add3_u32 v9, v8, v7, s1
	v_mul_f32_e32 v7, v229, v3
	v_exp_f32_e32 v10, v7
	v_addc_co_u32_e32 v7, vcc, 0, v5, vcc
	global_store_short_d16_hi v[6:7], v9, off
	v_mul_f32_e32 v7, v230, v3
	v_exp_f32_e32 v12, v7
	v_mul_f32_e32 v6, v176, v10
	v_mul_f32_e32 v11, v51, v6
	v_mul_f32_e32 v14, v231, v3
	v_mul_f32_e32 v13, v176, v12
	v_fmac_f32_e32 v11, v67, v10
	v_mul_f32_e32 v13, v52, v13
	v_exp_f32_e32 v14, v14
	v_bfe_u32 v6, v11, 16, 1
	s_mov_b32 s70, 0xfa02000
	v_fmac_f32_e32 v13, v68, v12
	v_add3_u32 v10, v11, v6, s1
	v_add_co_u32_e32 v6, vcc, s70, v4
	v_bfe_u32 v12, v13, 16, 1
	s_nop 0
	v_addc_co_u32_e32 v7, vcc, 0, v5, vcc
	v_add3_u32 v12, v13, v12, s1
	global_store_short_d16_hi v[6:7], v10, off offset:-4096
	global_store_short_d16_hi v[6:7], v12, off
	v_mul_f32_e32 v6, v176, v14
	v_mul_f32_e32 v15, v53, v6
	v_fmac_f32_e32 v15, v69, v14
	v_bfe_u32 v6, v15, 16, 1
	v_add3_u32 v14, v15, v6, s1
	v_mul_f32_e32 v6, v232, v3
	v_exp_f32_e32 v16, v6
	s_mov_b32 s70, 0xfa03000
	v_add_co_u32_e32 v6, vcc, s70, v4
	v_mul_f32_e32 v52, v234, v3
	s_nop 0
	v_addc_co_u32_e32 v7, vcc, 0, v5, vcc
	global_store_short_d16_hi v[6:7], v14, off
	v_mul_f32_e32 v6, v176, v16
	v_mul_f32_e32 v17, v54, v6
	v_fmac_f32_e32 v17, v70, v16
	v_bfe_u32 v6, v17, 16, 1
	v_add3_u32 v16, v17, v6, s1
	v_mul_f32_e32 v6, v233, v3
	v_exp_f32_e32 v50, v6
	v_exp_f32_e32 v52, v52
	s_mov_b32 s70, 0xfa09000
	v_add_co_u32_e32 v6, vcc, s70, v4
	v_mul_f32_e32 v51, v176, v50
	v_mul_f32_e32 v51, v55, v51
	v_fmac_f32_e32 v51, v71, v50
	v_bfe_u32 v50, v51, 16, 1
	v_addc_co_u32_e32 v7, vcc, 0, v5, vcc
	v_add3_u32 v50, v51, v50, s1
	global_store_short_d16_hi v[6:7], v16, off offset:-4096
	global_store_short_d16_hi v[6:7], v50, off
	v_mul_f32_e32 v6, v176, v52
	v_mul_f32_e32 v53, v56, v6
	v_fmac_f32_e32 v53, v72, v52
	v_bfe_u32 v6, v53, 16, 1
	v_add3_u32 v52, v53, v6, s1
	v_mul_f32_e32 v6, v235, v3
	v_exp_f32_e32 v54, v6
	v_mul_f32_e32 v56, v236, v3
	v_exp_f32_e32 v56, v56
	s_mov_b32 s70, 0xfa0b000
	v_mul_f32_e32 v55, v176, v54
	v_mul_f32_e32 v55, v57, v55
	v_fmac_f32_e32 v55, v73, v54
	v_add_co_u32_e32 v6, vcc, s70, v4
	v_bfe_u32 v54, v55, 16, 1
	s_nop 0
	v_addc_co_u32_e32 v7, vcc, 0, v5, vcc
	v_add3_u32 v54, v55, v54, s1
	global_store_short_d16_hi v[6:7], v52, off offset:-4096
	global_store_short_d16_hi v[6:7], v54, off
	v_mul_f32_e32 v6, v176, v56
	v_mul_f32_e32 v57, v58, v6
	v_fmac_f32_e32 v57, v74, v56
	v_bfe_u32 v6, v57, 16, 1
	v_add3_u32 v56, v57, v6, s1
	v_mul_f32_e32 v6, v237, v3
	v_exp_f32_e32 v58, v6
	s_mov_b32 s70, 0xfa11000
	v_add_co_u32_e32 v6, vcc, s70, v4
	v_mul_f32_e32 v66, v176, v58
	v_mul_f32_e32 v59, v59, v66
	v_mul_f32_e32 v66, v238, v3
	v_exp_f32_e32 v66, v66
	v_fmac_f32_e32 v59, v75, v58
	v_bfe_u32 v58, v59, 16, 1
	v_addc_co_u32_e32 v7, vcc, 0, v5, vcc
	v_add3_u32 v58, v59, v58, s1
	global_store_short_d16_hi v[6:7], v56, off offset:-4096
	global_store_short_d16_hi v[6:7], v58, off
	v_mul_f32_e32 v6, v176, v66
	v_mul_f32_e32 v60, v60, v6
	v_fmac_f32_e32 v60, v76, v66
	v_bfe_u32 v6, v60, 16, 1
	v_add3_u32 v66, v60, v6, s1
	v_mul_f32_e32 v6, v239, v3
	v_exp_f32_e32 v67, v6
	s_mov_b32 s70, 0xfa13000
	v_add_co_u32_e32 v6, vcc, s70, v4
	v_mul_f32_e32 v68, v176, v67
	v_mul_f32_e32 v61, v61, v68
	v_mul_f32_e32 v68, v240, v3
	v_exp_f32_e32 v68, v68
	v_fmac_f32_e32 v61, v77, v67
	v_bfe_u32 v67, v61, 16, 1
	v_addc_co_u32_e32 v7, vcc, 0, v5, vcc
	v_add3_u32 v67, v61, v67, s1
	global_store_short_d16_hi v[6:7], v66, off offset:-4096
	global_store_short_d16_hi v[6:7], v67, off
	v_mul_f32_e32 v6, v176, v68
	v_mul_f32_e32 v62, v62, v6
	v_fmac_f32_e32 v62, v78, v68
	v_bfe_u32 v6, v62, 16, 1
	v_add3_u32 v68, v62, v6, s1
	v_mul_f32_e32 v6, v241, v3
	v_exp_f32_e32 v69, v6
	s_mov_b32 s70, 0xfa19000
	v_add_co_u32_e32 v6, vcc, s70, v4
	v_mul_f32_e32 v70, v176, v69
	v_mul_f32_e32 v63, v63, v70
	v_mul_f32_e32 v70, v242, v3
	v_mul_f32_e32 v3, v243, v3
	v_exp_f32_e32 v70, v70
	v_exp_f32_e32 v3, v3
	v_fmac_f32_e32 v63, v79, v69
	v_bfe_u32 v69, v63, 16, 1
	v_addc_co_u32_e32 v7, vcc, 0, v5, vcc
	v_add3_u32 v69, v63, v69, s1
	global_store_short_d16_hi v[6:7], v68, off offset:-4096
	global_store_short_d16_hi v[6:7], v69, off
	v_mul_f32_e32 v7, v176, v70
	v_mul_f32_e32 v69, v176, v3
	v_mul_f32_e32 v7, v64, v7
	v_mul_f32_e32 v65, v65, v69
	v_fmac_f32_e32 v7, v80, v70
	s_mov_b32 s70, 0xfa1b000
	v_fmac_f32_e32 v65, v81, v3
	v_bfe_u32 v64, v7, 16, 1
	v_add_co_u32_e32 v4, vcc, s70, v4
	v_bfe_u32 v3, v65, 16, 1
	v_mul_f32_e32 v9, v8, v8
	v_mul_f32_e32 v10, v11, v11
	v_add3_u32 v64, v7, v64, s1
	v_addc_co_u32_e32 v5, vcc, 0, v5, vcc
	v_add3_u32 v3, v65, v3, s1
	v_mul_f32_e32 v12, v13, v13
	v_mul_f32_e32 v14, v15, v15
	v_mul_f32_e32 v16, v17, v17
	v_mul_f32_e32 v50, v51, v51
	global_store_short_d16_hi v[4:5], v64, off offset:-4096
	global_store_short_d16_hi v[4:5], v3, off
	v_mov_b32_dpp v4, v9 row_shr:1 row_mask:0xf bank_mask:0xf bound_ctrl:1
	v_mov_b32_dpp v5, v10 row_shr:1 row_mask:0xf bank_mask:0xf bound_ctrl:1
	v_mul_f32_e32 v52, v53, v53
	v_mul_f32_e32 v54, v55, v55
	v_mul_f32_e32 v56, v57, v57
	v_mul_f32_e32 v58, v59, v59
	v_mul_f32_e32 v66, v60, v60
	v_mul_f32_e32 v67, v61, v61
	v_mul_f32_e32 v68, v62, v62
	v_mul_f32_e32 v6, v63, v63
	v_mul_f32_e32 v64, v7, v7
	v_mul_f32_e32 v3, v65, v65
	v_fmac_f32_e32 v4, v8, v8
	v_fmac_f32_e32 v5, v11, v11
	v_mov_b32_dpp v8, v12 row_shr:1 row_mask:0xf bank_mask:0xf bound_ctrl:1
	v_mov_b32_dpp v9, v14 row_shr:1 row_mask:0xf bank_mask:0xf bound_ctrl:1
	v_mov_b32_dpp v10, v16 row_shr:1 row_mask:0xf bank_mask:0xf bound_ctrl:1
	v_mov_b32_dpp v11, v50 row_shr:1 row_mask:0xf bank_mask:0xf bound_ctrl:1
	v_fmac_f32_e32 v8, v13, v13
	v_fmac_f32_e32 v9, v15, v15
	v_fmac_f32_e32 v10, v17, v17
	v_fmac_f32_e32 v11, v51, v51
	v_mov_b32_dpp v12, v52 row_shr:1 row_mask:0xf bank_mask:0xf bound_ctrl:1
	v_mov_b32_dpp v13, v54 row_shr:1 row_mask:0xf bank_mask:0xf bound_ctrl:1
	v_mov_b32_dpp v14, v56 row_shr:1 row_mask:0xf bank_mask:0xf bound_ctrl:1
	v_mov_b32_dpp v15, v58 row_shr:1 row_mask:0xf bank_mask:0xf bound_ctrl:1
	v_mov_b32_dpp v16, v66 row_shr:1 row_mask:0xf bank_mask:0xf bound_ctrl:1
	v_mov_b32_dpp v17, v67 row_shr:1 row_mask:0xf bank_mask:0xf bound_ctrl:1
	v_mov_b32_dpp v50, v68 row_shr:1 row_mask:0xf bank_mask:0xf bound_ctrl:1
	v_mov_b32_dpp v6, v6 row_shr:1 row_mask:0xf bank_mask:0xf bound_ctrl:1
	v_mov_b32_dpp v51, v64 row_shr:1 row_mask:0xf bank_mask:0xf bound_ctrl:1
	v_mov_b32_dpp v3, v3 row_shr:1 row_mask:0xf bank_mask:0xf bound_ctrl:1
	v_fmac_f32_e32 v12, v53, v53
	v_fmac_f32_e32 v13, v55, v55
	v_fmac_f32_e32 v14, v57, v57
	v_fmac_f32_e32 v15, v59, v59
	v_fmac_f32_e32 v16, v60, v60
	v_fmac_f32_e32 v17, v61, v61
	v_fmac_f32_e32 v50, v62, v62
	v_fmac_f32_e32 v6, v63, v63
	v_fmac_f32_e32 v51, v7, v7
	v_fmac_f32_e32 v3, v65, v65
	v_add_f32_dpp v4, v4, v4 row_shr:2 row_mask:0xf bank_mask:0xf bound_ctrl:1
	v_add_f32_dpp v5, v5, v5 row_shr:2 row_mask:0xf bank_mask:0xf bound_ctrl:1
	v_add_f32_dpp v7, v8, v8 row_shr:2 row_mask:0xf bank_mask:0xf bound_ctrl:1
	v_add_f32_dpp v8, v9, v9 row_shr:2 row_mask:0xf bank_mask:0xf bound_ctrl:1
	v_add_f32_dpp v9, v10, v10 row_shr:2 row_mask:0xf bank_mask:0xf bound_ctrl:1
	v_add_f32_dpp v10, v11, v11 row_shr:2 row_mask:0xf bank_mask:0xf bound_ctrl:1
	v_add_f32_dpp v11, v12, v12 row_shr:2 row_mask:0xf bank_mask:0xf bound_ctrl:1
	v_add_f32_dpp v12, v13, v13 row_shr:2 row_mask:0xf bank_mask:0xf bound_ctrl:1
	v_add_f32_dpp v13, v14, v14 row_shr:2 row_mask:0xf bank_mask:0xf bound_ctrl:1
	v_add_f32_dpp v14, v15, v15 row_shr:2 row_mask:0xf bank_mask:0xf bound_ctrl:1
	v_add_f32_dpp v15, v16, v16 row_shr:2 row_mask:0xf bank_mask:0xf bound_ctrl:1
	v_add_f32_dpp v16, v17, v17 row_shr:2 row_mask:0xf bank_mask:0xf bound_ctrl:1
	v_add_f32_dpp v17, v50, v50 row_shr:2 row_mask:0xf bank_mask:0xf bound_ctrl:1
	v_add_f32_dpp v6, v6, v6 row_shr:2 row_mask:0xf bank_mask:0xf bound_ctrl:1
	v_add_f32_dpp v50, v51, v51 row_shr:2 row_mask:0xf bank_mask:0xf bound_ctrl:1
	v_add_f32_dpp v3, v3, v3 row_shr:2 row_mask:0xf bank_mask:0xf bound_ctrl:1
	v_add_f32_dpp v4, v4, v4 row_shr:4 row_mask:0xf bank_mask:0xf bound_ctrl:1
	v_add_f32_dpp v5, v5, v5 row_shr:4 row_mask:0xf bank_mask:0xf bound_ctrl:1
	v_add_f32_dpp v7, v7, v7 row_shr:4 row_mask:0xf bank_mask:0xf bound_ctrl:1
	v_add_f32_dpp v8, v8, v8 row_shr:4 row_mask:0xf bank_mask:0xf bound_ctrl:1
	v_add_f32_dpp v9, v9, v9 row_shr:4 row_mask:0xf bank_mask:0xf bound_ctrl:1
	v_add_f32_dpp v10, v10, v10 row_shr:4 row_mask:0xf bank_mask:0xf bound_ctrl:1
	v_add_f32_dpp v11, v11, v11 row_shr:4 row_mask:0xf bank_mask:0xf bound_ctrl:1
	v_add_f32_dpp v12, v12, v12 row_shr:4 row_mask:0xf bank_mask:0xf bound_ctrl:1
	v_add_f32_dpp v13, v13, v13 row_shr:4 row_mask:0xf bank_mask:0xf bound_ctrl:1
	v_add_f32_dpp v14, v14, v14 row_shr:4 row_mask:0xf bank_mask:0xf bound_ctrl:1
	v_add_f32_dpp v15, v15, v15 row_shr:4 row_mask:0xf bank_mask:0xf bound_ctrl:1
	v_add_f32_dpp v16, v16, v16 row_shr:4 row_mask:0xf bank_mask:0xf bound_ctrl:1
	v_add_f32_dpp v17, v17, v17 row_shr:4 row_mask:0xf bank_mask:0xf bound_ctrl:1
	v_add_f32_dpp v51, v6, v6 row_shr:4 row_mask:0xf bank_mask:0xf bound_ctrl:1
	v_add_f32_dpp v53, v50, v50 row_shr:4 row_mask:0xf bank_mask:0xf bound_ctrl:1
	v_add_f32_dpp v54, v3, v3 row_shr:4 row_mask:0xf bank_mask:0xf bound_ctrl:1
	v_add_f32_dpp v3, v4, v4 row_shr:8 row_mask:0xf bank_mask:0xf bound_ctrl:1
	v_add_f32_dpp v4, v5, v5 row_shr:8 row_mask:0xf bank_mask:0xf bound_ctrl:1
	v_add_f32_dpp v5, v7, v7 row_shr:8 row_mask:0xf bank_mask:0xf bound_ctrl:1
	v_add_f32_dpp v6, v8, v8 row_shr:8 row_mask:0xf bank_mask:0xf bound_ctrl:1
	v_add_f32_dpp v7, v9, v9 row_shr:8 row_mask:0xf bank_mask:0xf bound_ctrl:1
	v_add_f32_dpp v8, v10, v10 row_shr:8 row_mask:0xf bank_mask:0xf bound_ctrl:1
	v_add_f32_dpp v9, v11, v11 row_shr:8 row_mask:0xf bank_mask:0xf bound_ctrl:1
	v_add_f32_dpp v10, v12, v12 row_shr:8 row_mask:0xf bank_mask:0xf bound_ctrl:1
	v_add_f32_dpp v11, v13, v13 row_shr:8 row_mask:0xf bank_mask:0xf bound_ctrl:1
	v_add_f32_dpp v13, v14, v14 row_shr:8 row_mask:0xf bank_mask:0xf bound_ctrl:1
	v_add_f32_dpp v15, v15, v15 row_shr:8 row_mask:0xf bank_mask:0xf bound_ctrl:1
	v_add_f32_dpp v16, v16, v16 row_shr:8 row_mask:0xf bank_mask:0xf bound_ctrl:1
	v_add_f32_dpp v50, v17, v17 row_shr:8 row_mask:0xf bank_mask:0xf bound_ctrl:1
	v_add_f32_dpp v52, v51, v51 row_shr:8 row_mask:0xf bank_mask:0xf bound_ctrl:1
	v_add_f32_dpp v53, v53, v53 row_shr:8 row_mask:0xf bank_mask:0xf bound_ctrl:1
	v_add_f32_dpp v55, v54, v54 row_shr:8 row_mask:0xf bank_mask:0xf bound_ctrl:1
	v_mov_b32_e32 v12, 0
	v_mov_b32_e32 v14, 0
	v_mov_b32_e32 v17, 0
	v_mov_b32_e32 v51, 0
	v_mov_b32_e32 v54, 0
	v_mov_b32_e32 v56, 0
	v_mov_b32_e32 v57, 0
	v_mov_b32_e32 v58, 0
	v_mov_b32_e32 v59, 0
	v_mov_b32_e32 v60, 0
	v_mov_b32_e32 v61, 0
	v_mov_b32_e32 v62, 0
	v_mov_b32_e32 v63, 0
	v_mov_b32_e32 v64, 0
	v_mov_b32_e32 v65, 0
	v_mov_b32_e32 v66, 0
	v_mov_b32_dpp v12, v3 row_bcast:15 row_mask:0xa bank_mask:0xf bound_ctrl:1
	v_mov_b32_dpp v14, v4 row_bcast:15 row_mask:0xa bank_mask:0xf bound_ctrl:1
	v_mov_b32_dpp v17, v5 row_bcast:15 row_mask:0xa bank_mask:0xf bound_ctrl:1
	v_mov_b32_dpp v51, v6 row_bcast:15 row_mask:0xa bank_mask:0xf bound_ctrl:1
	v_mov_b32_dpp v54, v7 row_bcast:15 row_mask:0xa bank_mask:0xf bound_ctrl:1
	v_mov_b32_dpp v56, v8 row_bcast:15 row_mask:0xa bank_mask:0xf bound_ctrl:1
	v_mov_b32_dpp v57, v9 row_bcast:15 row_mask:0xa bank_mask:0xf bound_ctrl:1
	v_mov_b32_dpp v58, v10 row_bcast:15 row_mask:0xa bank_mask:0xf bound_ctrl:1
	v_mov_b32_dpp v59, v11 row_bcast:15 row_mask:0xa bank_mask:0xf bound_ctrl:1
	v_mov_b32_dpp v60, v13 row_bcast:15 row_mask:0xa bank_mask:0xf bound_ctrl:1
	v_mov_b32_dpp v61, v15 row_bcast:15 row_mask:0xa bank_mask:0xf bound_ctrl:1
	v_mov_b32_dpp v62, v16 row_bcast:15 row_mask:0xa bank_mask:0xf bound_ctrl:1
	v_mov_b32_dpp v63, v50 row_bcast:15 row_mask:0xa bank_mask:0xf bound_ctrl:1
	v_mov_b32_dpp v64, v52 row_bcast:15 row_mask:0xa bank_mask:0xf bound_ctrl:1
	v_mov_b32_dpp v65, v53 row_bcast:15 row_mask:0xa bank_mask:0xf bound_ctrl:1
	v_mov_b32_dpp v66, v55 row_bcast:15 row_mask:0xa bank_mask:0xf bound_ctrl:1
	s_and_saveexec_b64 s[70:71], s[2:3]
	s_cbranch_execz .LBB0_592
	v_add_f32_e32 v17, v5, v17
	v_add_f32_e32 v14, v4, v14
	v_lshl_add_u64 v[4:5], s[82:83], 0, v[182:183]
	s_mov_b32 s74, 0x200000
	v_add_f32_e32 v51, v6, v51
	v_add_co_u32_e32 v6, vcc, s74, v4
	v_add_f32_e32 v54, v7, v54
	s_nop 0
	v_addc_co_u32_e32 v7, vcc, 0, v5, vcc
	v_add_co_u32_e32 v4, vcc, 0x201000, v4
	v_add_f32_e32 v11, v11, v59
	v_add_f32_e32 v3, v3, v12
	v_addc_co_u32_e32 v5, vcc, 0, v5, vcc
	v_add_f32_e32 v55, v55, v66
	v_add_f32_e32 v53, v53, v65
	v_add_f32_e32 v52, v52, v64
	v_add_f32_e32 v50, v50, v63
	v_add_f32_e32 v16, v16, v62
	v_add_f32_e32 v15, v15, v61
	v_add_f32_e32 v13, v13, v60
	v_add_f32_e32 v10, v10, v58
	v_add_f32_e32 v9, v9, v57
	v_add_f32_e32 v8, v8, v56
	global_store_dword v[6:7], v3, off
	global_store_dword v[6:7], v14, off offset:256
	global_store_dword v[6:7], v17, off offset:512
	global_store_dword v[6:7], v51, off offset:768
	global_store_dword v[6:7], v54, off offset:2048
	global_store_dword v[6:7], v8, off offset:2304
	global_store_dword v[6:7], v9, off offset:2560
	global_store_dword v[6:7], v10, off offset:2816
	global_store_dword v[4:5], v11, off
	global_store_dword v[4:5], v13, off offset:256
	global_store_dword v[4:5], v15, off offset:512
	global_store_dword v[4:5], v16, off offset:768
	global_store_dword v[4:5], v50, off offset:2048
	global_store_dword v[4:5], v52, off offset:2304
	global_store_dword v[4:5], v53, off offset:2560
	global_store_dword v[4:5], v55, off offset:2816
	s_branch .LBB0_592
.LBB0_616:
	v_readlane_b32 s74, v255, 12
	v_readlane_b32 s75, v255, 13
	s_load_dwordx2 s[92:93], s[74:75], 0x88
	v_readlane_b32 s91, v255, 14
	v_readlane_b32 s90, v255, 11
